# v40 stack + aligned epilogues in P5 (was staggered)
# speedup vs baseline: 1.0152x; 1.0152x over previous
;     __device__ __forceinline__ void operator()(const f32x4 (&acc)[2][2][4][2], const Unit& u, int wr, int wc, int fr, int fq) const {
;         const int row0 = u.pm * BM + wr * 64 + fr, col0 = u.pn * BM + wc * 32 + 8 * fq;
;         f32x4 sp[2][4];
; #pragma unroll
;         for (int ai = 0; ai < 2; ++ai)
; #pragma unroll
;             for (int m = 0; m < 4; ++m) sp[ai][m] = *(const f32x4*)(ssq + (size_t)(row0 + ai * HALF + m * 16) * 16 + 4 * fq);
; #pragma unroll
;         for (int ai = 0; ai < 2; ++ai)
; #pragma unroll
;             for (int m = 0; m < 4; ++m) { const int row = row0 + ai * HALF + m * 16;
;                 float t = (sp[ai][m][0] + sp[ai][m][1]) + (sp[ai][m][2] + sp[ai][m][3]); t += __shfl_xor(t, 16); t += __shfl_xor(t, 32);
;                 const float rs = rsqrtf(t * (1.0f / DM) + EPS);
; template <class Epi, class SchedT, bool ALIGN_EPI, bool SP2, bool FP8 = false>
; __device__ __forceinline__ void gemm_phase(LAS unsigned char* lds, const Gemm g, const SchedT& S, const Epi& E, const int wid) {
;     ...
; #pragma unroll
;         for (int a = 0; a < 2; ++a)
; #pragma unroll
;             for (int b = 0; b < 2; ++b)
; #pragma unroll
;                 for (int m = 0; m < 4; ++m)
; #pragma unroll
;                     for (int n = 0; n < 2; ++n) acc[a][b][m][n] = (f32x4){0.f, 0.f, 0.f, 0.f};
.LBB0_893:
	v_mov_b32_e32 v127, 0
	v_mov_b32_e32 v126, v127
	v_mov_b32_e32 v125, v127
	v_mov_b32_e32 v124, v127
	v_mov_b32_e32 v123, v127
	v_mov_b32_e32 v122, v127
	v_mov_b32_e32 v121, v127
	v_mov_b32_e32 v120, v127
	v_mov_b32_e32 v111, v127
	v_mov_b32_e32 v110, v127
	v_mov_b32_e32 v109, v127
	v_mov_b32_e32 v108, v127
	v_mov_b32_e32 v107, v127
	v_mov_b32_e32 v106, v127
	v_mov_b32_e32 v105, v127
	v_mov_b32_e32 v104, v127
	v_mov_b32_e32 v95, v127
	v_mov_b32_e32 v94, v127
	v_mov_b32_e32 v93, v127
	v_mov_b32_e32 v92, v127
	v_mov_b32_e32 v91, v127
	v_mov_b32_e32 v90, v127
	v_mov_b32_e32 v89, v127
	v_mov_b32_e32 v88, v127
	v_mov_b32_e32 v79, v127
	v_mov_b32_e32 v78, v127
	v_mov_b32_e32 v77, v127
	v_mov_b32_e32 v76, v127
	v_mov_b32_e32 v75, v127
	v_mov_b32_e32 v74, v127
	v_mov_b32_e32 v73, v127
	v_mov_b32_e32 v72, v127
	v_mov_b32_e32 v119, v127
	v_mov_b32_e32 v118, v127
	v_mov_b32_e32 v117, v127
	v_mov_b32_e32 v116, v127
	v_mov_b32_e32 v115, v127
	v_mov_b32_e32 v114, v127
	v_mov_b32_e32 v113, v127
	v_mov_b32_e32 v112, v127
	v_mov_b32_e32 v103, v127
	v_mov_b32_e32 v102, v127
	v_mov_b32_e32 v101, v127
	v_mov_b32_e32 v100, v127
	v_mov_b32_e32 v99, v127
	v_mov_b32_e32 v98, v127
	v_mov_b32_e32 v97, v127
	v_mov_b32_e32 v96, v127
	v_mov_b32_e32 v87, v127
	v_mov_b32_e32 v86, v127
	v_mov_b32_e32 v85, v127
	v_mov_b32_e32 v84, v127
	v_mov_b32_e32 v83, v127
	v_mov_b32_e32 v82, v127
	v_mov_b32_e32 v81, v127
	v_mov_b32_e32 v80, v127
	v_mov_b32_e32 v71, v127
	v_mov_b32_e32 v70, v127
	v_mov_b32_e32 v69, v127
	v_mov_b32_e32 v68, v127
	v_mov_b32_e32 v67, v127
	v_mov_b32_e32 v66, v127
	v_mov_b32_e32 v65, v127
	v_mov_b32_e32 v64, v127
	v_mov_b32_e32 v63, v127
	v_mov_b32_e32 v62, v127
	v_mov_b32_e32 v61, v127
	v_mov_b32_e32 v60, v127
	v_mov_b32_e32 v59, v127
	v_mov_b32_e32 v58, v127
	v_mov_b32_e32 v57, v127
	v_mov_b32_e32 v56, v127
	v_mov_b32_e32 v47, v127
	v_mov_b32_e32 v46, v127
	v_mov_b32_e32 v45, v127
	v_mov_b32_e32 v44, v127
	v_mov_b32_e32 v43, v127
	v_mov_b32_e32 v42, v127
	v_mov_b32_e32 v41, v127
	v_mov_b32_e32 v40, v127
	v_mov_b32_e32 v31, v127
	v_mov_b32_e32 v30, v127
	v_mov_b32_e32 v29, v127
	v_mov_b32_e32 v28, v127
	v_mov_b32_e32 v27, v127
	v_mov_b32_e32 v26, v127
	v_mov_b32_e32 v25, v127
	v_mov_b32_e32 v24, v127
	v_mov_b32_e32 v15, v127
	v_mov_b32_e32 v14, v127
	v_mov_b32_e32 v13, v127
	v_mov_b32_e32 v12, v127
	v_mov_b32_e32 v11, v127
	v_mov_b32_e32 v10, v127
	v_mov_b32_e32 v9, v127
	v_mov_b32_e32 v8, v127
	v_mov_b32_e32 v55, v127
	v_mov_b32_e32 v54, v127
	v_mov_b32_e32 v53, v127
	v_mov_b32_e32 v52, v127
	v_mov_b32_e32 v51, v127
	v_mov_b32_e32 v50, v127
	v_mov_b32_e32 v49, v127
	v_mov_b32_e32 v48, v127
	v_mov_b32_e32 v39, v127
	v_mov_b32_e32 v38, v127
	v_mov_b32_e32 v37, v127
	v_mov_b32_e32 v36, v127
	v_mov_b32_e32 v35, v127
	v_mov_b32_e32 v34, v127
	v_mov_b32_e32 v33, v127
	v_mov_b32_e32 v32, v127
	v_mov_b32_e32 v23, v127
	v_mov_b32_e32 v22, v127
	v_mov_b32_e32 v21, v127
	v_mov_b32_e32 v20, v127
	v_mov_b32_e32 v19, v127
	v_mov_b32_e32 v18, v127
	v_mov_b32_e32 v17, v127
	v_mov_b32_e32 v16, v127
	v_mov_b32_e32 v7, v127
	v_mov_b32_e32 v6, v127
	v_mov_b32_e32 v5, v127
	v_mov_b32_e32 v4, v127
	v_mov_b32_e32 v3, v127
	v_mov_b32_e32 v2, v127
	v_mov_b32_e32 v1, v127
	v_mov_b32_e32 v0, v127
.LBB0_894:
	s_and_b64 vcc, exec, s[96:97]
	s_cbranch_vccz .Lp5_al_pre
	s_barrier
.Lp5_al_pre:
	s_lshl_b32 s15, s46, 8
	s_add_i32 s15, s15, s91
	v_mbcnt_lo_u32_b32 v128, -1, 0
	v_mbcnt_hi_u32_b32 v128, -1, v128
	v_and_b32_e32 v142, 64, v180
	v_ashrrev_i32_e32 v140, 4, v128
	v_and_or_b32 v136, v128, 15, s15
	v_lshlrev_b32_e32 v128, 2, v140
	v_or_b32_e32 v166, 16, v136
	v_ashrrev_i32_e32 v129, 31, v128
	v_ashrrev_i32_e32 v137, 31, v136
	v_ashrrev_i32_e32 v167, 31, v166
	v_lshl_add_u64 v[138:139], v[128:129], 2, s[10:11]
	v_lshlrev_b64 v[128:129], 6, v[136:137]
	v_lshlrev_b64 v[132:133], 6, v[166:167]
	v_lshl_add_u64 v[128:129], v[138:139], 0, v[128:129]
	v_lshl_add_u64 v[132:133], v[138:139], 0, v[132:133]
	global_load_dwordx4 v[128:131], v[128:129], off
	s_lshl_b32 s15, s44, 8
	global_load_dwordx4 v[132:135], v[132:133], off
	v_xor_b32_e32 v141, 16, v180
	v_add_u32_e32 v142, 64, v142
	s_or_b32 s15, s15, s78
	v_cmp_lt_i32_e32 vcc, v141, v142
	v_xor_b32_e32 v143, 32, v180
	v_lshl_add_u32 v140, v140, 3, s15
	v_cndmask_b32_e32 v141, v180, v141, vcc
	v_or_b32_e32 v164, 32, v136
	v_cmp_lt_i32_e32 vcc, v143, v142
	v_or_b32_e32 v162, 48, v136
	v_add_u32_e32 v160, 0x80, v136
	v_add_u32_e32 v158, 0x90, v136
	v_add_u32_e32 v156, 0xa0, v136
	v_add_u32_e32 v150, 0xb0, v136
	v_lshlrev_b32_e32 v181, 2, v141
	v_ashrrev_i32_e32 v141, 31, v140
	v_ashrrev_i32_e32 v165, 31, v164
	v_cndmask_b32_e32 v142, v180, v143, vcc
	v_ashrrev_i32_e32 v163, 31, v162
	v_ashrrev_i32_e32 v161, 31, v160
	v_ashrrev_i32_e32 v159, 31, v158
	v_ashrrev_i32_e32 v157, 31, v156
	v_ashrrev_i32_e32 v151, 31, v150
	v_lshlrev_b64 v[152:153], 1, v[140:141]
	v_lshlrev_b64 v[140:141], 6, v[164:165]
	v_lshlrev_b32_e32 v144, 2, v142
	v_lshlrev_b64 v[142:143], 6, v[162:163]
	v_lshlrev_b64 v[182:183], 6, v[160:161]
	v_lshlrev_b64 v[184:185], 6, v[158:159]
	v_lshlrev_b64 v[186:187], 6, v[156:157]
	v_lshlrev_b64 v[188:189], 6, v[150:151]
	v_lshl_add_u64 v[140:141], v[138:139], 0, v[140:141]
	v_lshl_add_u64 v[192:193], v[138:139], 0, v[186:187]
	v_lshl_add_u64 v[194:195], v[138:139], 0, v[188:189]
	v_mov_b64_e32 v[154:155], s[12:13]
	v_lshlrev_b64 v[136:137], 13, v[136:137]
	v_lshl_add_u64 v[136:137], s[36:37], 0, v[136:137]
	v_lshl_add_u64 v[196:197], v[136:137], 0, v[152:153]
	s_mov_b32 s44, s14
	s_mov_b32 s46, s26
	s_mov_b32 s20, s23
	s_mov_b64 s[50:51], s[42:43]
	s_mov_b64 s[48:49], s[40:41]
	s_waitcnt vmcnt(0)
; __device__ __forceinline__ unsigned pk2(float lo, float hi) { f32x2_t v = {lo, hi}; bf16x2_t b = __builtin_convertvector(v, bf16x2_t); return __builtin_bit_cast(unsigned, b); }
;     __device__ __forceinline__ void operator()(const f32x4 (&acc)[2][2][4][2], const Unit& u, int wr, int wc, int fr, int fq) const {
;     ...
;             for (int m = 0; m < 4; ++m) sp[ai][m] = *(const f32x4*)(ssq + (size_t)(row0 + ai * HALF + m * 16) * 16 + 4 * fq);
; #pragma unroll
;         for (int ai = 0; ai < 2; ++ai)
; #pragma unroll
;             for (int m = 0; m < 4; ++m) { const int row = row0 + ai * HALF + m * 16;
;                 float t = (sp[ai][m][0] + sp[ai][m][1]) + (sp[ai][m][2] + sp[ai][m][3]); t += __shfl_xor(t, 16); t += __shfl_xor(t, 32);
;                 const float rs = rsqrtf(t * (1.0f / DM) + EPS);
;                 bf16_t* rowp = O + (size_t)row * DFF + col0;
; #pragma unroll
;                 for (int bj = 0; bj < 2; ++bj) { f32x4 v0 = acc[ai][bj][m][0] * rs, v1 = acc[ai][bj][m][1] * rs;
; #pragma unroll
;                     for (int e = 0; e < 4; ++e) { v0[e] = fmaxf(v0[e], 0.f); v0[e] *= v0[e]; v1[e] = fmaxf(v1[e], 0.f); v1[e] *= v1[e]; }
;                     u32x4 w; w.x = pk2(v0[0], v0[1]); w.y = pk2(v0[2], v0[3]); w.z = pk2(v1[0], v1[1]); w.w = pk2(v1[2], v1[3]);
;                     *(u32x4*)(rowp + bj * HALF) = w; } }
	v_mov_b32_e32 v190, v129
	v_mov_b32_e32 v191, v130
	v_mov_b32_e32 v129, v131
	v_mov_b32_e32 v130, v133
	v_mov_b32_e32 v131, v134
	v_mov_b32_e32 v133, v135
	v_pk_add_f32 v[128:129], v[190:191], v[128:129]
	v_pk_add_f32 v[130:131], v[130:131], v[132:133]
	v_mov_b32_e32 v133, v128
	v_mov_b32_e32 v132, v130
	v_mov_b32_e32 v128, v131
	v_pk_add_f32 v[128:129], v[132:133], v[128:129]
	v_lshl_add_u64 v[132:133], v[138:139], 0, v[142:143]
	v_lshl_add_u64 v[134:135], v[138:139], 0, v[182:183]
	v_lshl_add_u64 v[190:191], v[138:139], 0, v[184:185]
	global_load_dwordx4 v[182:185], v[140:141], off
	global_load_dwordx4 v[186:189], v[132:133], off
	ds_bpermute_b32 v131, v181, v129
	ds_bpermute_b32 v130, v181, v128
	s_waitcnt lgkmcnt(0)
	v_pk_add_f32 v[128:129], v[128:129], v[130:131]
	ds_bpermute_b32 v131, v144, v129
	ds_bpermute_b32 v130, v144, v128
	s_waitcnt lgkmcnt(0)
	v_pk_add_f32 v[128:129], v[128:129], v[130:131]
	s_nop 0
	v_pk_fma_f32 v[198:199], v[128:129], s[8:9], v[154:155] op_sel_hi:[1,0,0]
	s_nop 0
	v_mul_f32_e32 v128, 0x4b800000, v199
	v_cmp_gt_f32_e32 vcc, s22, v199
	s_nop 1
	v_cndmask_b32_e32 v128, v199, v128, vcc
	v_rsq_f32_e32 v199, v128
	global_load_dwordx4 v[140:143], v[134:135], off
	global_load_dwordx4 v[136:139], v[190:191], off
	s_nop 0
	global_load_dwordx4 v[132:135], v[192:193], off
	global_load_dwordx4 v[128:131], v[194:195], off
	v_mul_f32_e32 v190, 0x45800000, v199
	v_cndmask_b32_e32 v190, v199, v190, vcc
	v_pk_mul_f32 v[126:127], v[126:127], v[190:191] op_sel_hi:[1,0]
	v_pk_mul_f32 v[124:125], v[124:125], v[190:191] op_sel_hi:[1,0]
	v_pk_mul_f32 v[122:123], v[122:123], v[190:191] op_sel_hi:[1,0]
	v_pk_mul_f32 v[120:121], v[120:121], v[190:191] op_sel_hi:[1,0]
	v_pk_mul_f32 v[118:119], v[118:119], v[190:191] op_sel_hi:[1,0]
	v_pk_mul_f32 v[116:117], v[116:117], v[190:191] op_sel_hi:[1,0]
	v_pk_mul_f32 v[192:193], v[114:115], v[190:191] op_sel_hi:[1,0]
	v_pk_mul_f32 v[190:191], v[112:113], v[190:191] op_sel_hi:[1,0]
	v_max_f32_e32 v112, 0, v124
	v_max_f32_e32 v114, 0, v120
	v_max_f32_e32 v113, 0, v125
	v_max_f32_e32 v115, 0, v121
	v_max_f32_e32 v120, 0, v126
	v_max_f32_e32 v122, 0, v122
	v_max_f32_e32 v121, 0, v127
	v_max_f32_e32 v123, 0, v123
	v_pk_mul_f32 v[112:113], v[112:113], v[112:113]
	v_pk_mul_f32 v[114:115], v[114:115], v[114:115]
	v_pk_mul_f32 v[120:121], v[120:121], v[120:121]
	v_pk_mul_f32 v[122:123], v[122:123], v[122:123]
	v_cvt_pk_bf16_f32 v112, v112, v113
	v_cvt_pk_bf16_f32 v113, v120, v121
	v_cvt_pk_bf16_f32 v114, v114, v115
	v_cvt_pk_bf16_f32 v115, v122, v123
	v_max_f32_e32 v116, 0, v116
	global_store_dwordx4 v[196:197], v[112:115], off
	v_max_f32_e32 v117, 0, v117
	v_cmp_gt_f32_e32 vcc, s22, v198
	v_max_f32_e32 v112, 0, v190
	v_max_f32_e32 v113, 0, v191
	v_pk_mul_f32 v[114:115], v[116:117], v[116:117]
	v_pk_mul_f32 v[116:117], v[112:113], v[112:113]
	v_max_f32_e32 v112, 0, v118
	v_max_f32_e32 v113, 0, v119
	v_pk_mul_f32 v[120:121], v[112:113], v[112:113]
	v_cvt_pk_bf16_f32 v112, v114, v115
	v_mul_f32_e32 v114, 0x4b800000, v198
	v_cndmask_b32_e32 v114, v198, v114, vcc
	v_cvt_pk_bf16_f32 v113, v120, v121
	v_rsq_f32_e32 v120, v114
	v_max_f32_e32 v118, 0, v192
	v_max_f32_e32 v119, 0, v193
	v_pk_mul_f32 v[118:119], v[118:119], v[118:119]
	v_cvt_pk_bf16_f32 v114, v116, v117
	v_cvt_pk_bf16_f32 v115, v118, v119
	global_store_dwordx4 v[196:197], v[112:115], off offset:256
	s_nop 1
	v_mul_f32_e32 v112, 0x45800000, v120
	v_cndmask_b32_e32 v112, v120, v112, vcc
	v_pk_mul_f32 v[104:105], v[104:105], v[112:113] op_sel_hi:[1,0]
	v_pk_mul_f32 v[110:111], v[110:111], v[112:113] op_sel_hi:[1,0]
	v_pk_mul_f32 v[108:109], v[108:109], v[112:113] op_sel_hi:[1,0]
	v_pk_mul_f32 v[106:107], v[106:107], v[112:113] op_sel_hi:[1,0]
	v_max_f32_e32 v104, 0, v104
	v_max_f32_e32 v105, 0, v105
	v_lshlrev_b64 v[114:115], 13, v[166:167]
	v_max_f32_e32 v108, 0, v108
	v_max_f32_e32 v109, 0, v109
	v_pk_mul_f32 v[116:117], v[104:105], v[104:105]
	v_max_f32_e32 v104, 0, v110
	v_max_f32_e32 v106, 0, v106
	v_max_f32_e32 v105, 0, v111
	v_max_f32_e32 v107, 0, v107
	v_lshl_add_u64 v[114:115], s[36:37], 0, v[114:115]
	v_pk_mul_f32 v[108:109], v[108:109], v[108:109]
	v_pk_mul_f32 v[110:111], v[104:105], v[104:105]
	v_pk_mul_f32 v[118:119], v[106:107], v[106:107]
	v_pk_mul_f32 v[96:97], v[96:97], v[112:113] op_sel_hi:[1,0]
	v_lshl_add_u64 v[114:115], v[114:115], 0, v[152:153]
	v_cvt_pk_bf16_f32 v104, v108, v109
	v_cvt_pk_bf16_f32 v105, v110, v111
	v_cvt_pk_bf16_f32 v106, v116, v117
	v_cvt_pk_bf16_f32 v107, v118, v119
	v_pk_mul_f32 v[102:103], v[102:103], v[112:113] op_sel_hi:[1,0]
	v_max_f32_e32 v96, 0, v96
	v_max_f32_e32 v97, 0, v97
	global_store_dwordx4 v[114:115], v[104:107], off
	v_pk_mul_f32 v[100:101], v[100:101], v[112:113] op_sel_hi:[1,0]
	v_pk_mul_f32 v[98:99], v[98:99], v[112:113] op_sel_hi:[1,0]
	v_pk_mul_f32 v[104:105], v[96:97], v[96:97]
	v_max_f32_e32 v96, 0, v102
	v_max_f32_e32 v97, 0, v103
	s_waitcnt vmcnt(8)
	v_mov_b32_e32 v102, v183
	v_mov_b32_e32 v103, v184
	v_mov_b32_e32 v183, v185
	s_waitcnt vmcnt(7)
	v_mov_b32_e32 v106, v187
	v_mov_b32_e32 v107, v188
	v_mov_b32_e32 v187, v189
	v_pk_add_f32 v[102:103], v[102:103], v[182:183]
	v_pk_add_f32 v[106:107], v[106:107], v[186:187]
	v_mov_b32_e32 v109, v102
	v_mov_b32_e32 v108, v106
	v_mov_b32_e32 v102, v107
	v_pk_add_f32 v[102:103], v[108:109], v[102:103]
	ds_bpermute_b32 v107, v181, v103
	ds_bpermute_b32 v106, v181, v102
	v_max_f32_e32 v100, 0, v100
	v_max_f32_e32 v101, 0, v101
	v_pk_mul_f32 v[100:101], v[100:101], v[100:101]
	v_pk_mul_f32 v[108:109], v[96:97], v[96:97]
	v_cvt_pk_bf16_f32 v96, v100, v101
	s_waitcnt lgkmcnt(0)
; __device__ __forceinline__ unsigned pk2(float lo, float hi) { f32x2_t v = {lo, hi}; bf16x2_t b = __builtin_convertvector(v, bf16x2_t); return __builtin_bit_cast(unsigned, b); }
;     __device__ __forceinline__ void operator()(const f32x4 (&acc)[2][2][4][2], const Unit& u, int wr, int wc, int fr, int fq) const {
;     ...
;             for (int m = 0; m < 4; ++m) { const int row = row0 + ai * HALF + m * 16;
;                 float t = (sp[ai][m][0] + sp[ai][m][1]) + (sp[ai][m][2] + sp[ai][m][3]); t += __shfl_xor(t, 16); t += __shfl_xor(t, 32);
;                 const float rs = rsqrtf(t * (1.0f / DM) + EPS);
;                 bf16_t* rowp = O + (size_t)row * DFF + col0;
; #pragma unroll
;                 for (int bj = 0; bj < 2; ++bj) { f32x4 v0 = acc[ai][bj][m][0] * rs, v1 = acc[ai][bj][m][1] * rs;
; #pragma unroll
;                     for (int e = 0; e < 4; ++e) { v0[e] = fmaxf(v0[e], 0.f); v0[e] *= v0[e]; v1[e] = fmaxf(v1[e], 0.f); v1[e] *= v1[e]; }
;                     u32x4 w; w.x = pk2(v0[0], v0[1]); w.y = pk2(v0[2], v0[3]); w.z = pk2(v1[0], v1[1]); w.w = pk2(v1[2], v1[3]);
;                     *(u32x4*)(rowp + bj * HALF) = w; } }
	v_pk_add_f32 v[100:101], v[102:103], v[106:107]
	ds_bpermute_b32 v103, v144, v101
	ds_bpermute_b32 v102, v144, v100
	v_max_f32_e32 v98, 0, v98
	v_max_f32_e32 v99, 0, v99
	v_pk_mul_f32 v[110:111], v[98:99], v[98:99]
	v_cvt_pk_bf16_f32 v97, v108, v109
	v_cvt_pk_bf16_f32 v98, v104, v105
	v_cvt_pk_bf16_f32 v99, v110, v111
	global_store_dwordx4 v[114:115], v[96:99], off offset:256
	s_waitcnt lgkmcnt(0)
	s_nop 0
	v_pk_add_f32 v[96:97], v[100:101], v[102:103]
	s_nop 0
	v_pk_fma_f32 v[96:97], v[96:97], s[8:9], v[154:155] op_sel_hi:[1,0,0]
	s_nop 0
	v_mul_f32_e32 v98, 0x4b800000, v97
	v_cmp_gt_f32_e32 vcc, s22, v97
	s_nop 1
	v_cndmask_b32_e32 v97, v97, v98, vcc
	v_rsq_f32_e32 v97, v97
	v_lshlrev_b64 v[98:99], 13, v[164:165]
	v_lshl_add_u64 v[98:99], s[36:37], 0, v[98:99]
	v_lshl_add_u64 v[98:99], v[98:99], 0, v[152:153]
	v_mul_f32_e32 v100, 0x45800000, v97
	v_cndmask_b32_e32 v100, v97, v100, vcc
	v_pk_mul_f32 v[88:89], v[88:89], v[100:101] op_sel_hi:[1,0]
	v_pk_mul_f32 v[94:95], v[94:95], v[100:101] op_sel_hi:[1,0]
	v_pk_mul_f32 v[92:93], v[92:93], v[100:101] op_sel_hi:[1,0]
	v_pk_mul_f32 v[90:91], v[90:91], v[100:101] op_sel_hi:[1,0]
	v_max_f32_e32 v88, 0, v88
	v_max_f32_e32 v89, 0, v89
	v_max_f32_e32 v92, 0, v92
	v_max_f32_e32 v93, 0, v93
	v_pk_mul_f32 v[102:103], v[88:89], v[88:89]
	v_max_f32_e32 v88, 0, v94
	v_max_f32_e32 v90, 0, v90
	v_max_f32_e32 v89, 0, v95
	v_max_f32_e32 v91, 0, v91
	v_pk_mul_f32 v[92:93], v[92:93], v[92:93]
	v_pk_mul_f32 v[94:95], v[88:89], v[88:89]
	v_pk_mul_f32 v[104:105], v[90:91], v[90:91]
	v_pk_mul_f32 v[82:83], v[82:83], v[100:101] op_sel_hi:[1,0]
	v_cvt_pk_bf16_f32 v88, v92, v93
	v_cvt_pk_bf16_f32 v89, v94, v95
	v_cvt_pk_bf16_f32 v90, v102, v103
	v_cvt_pk_bf16_f32 v91, v104, v105
	v_pk_mul_f32 v[84:85], v[84:85], v[100:101] op_sel_hi:[1,0]
	v_pk_mul_f32 v[80:81], v[80:81], v[100:101] op_sel_hi:[1,0]
	v_max_f32_e32 v82, 0, v82
	v_max_f32_e32 v83, 0, v83
	global_store_dwordx4 v[98:99], v[88:91], off
	v_pk_mul_f32 v[86:87], v[86:87], v[100:101] op_sel_hi:[1,0]
	v_max_f32_e32 v84, 0, v84
	v_max_f32_e32 v80, 0, v80
	v_max_f32_e32 v85, 0, v85
	v_max_f32_e32 v81, 0, v81
	v_pk_mul_f32 v[90:91], v[82:83], v[82:83]
	v_mul_f32_e32 v82, 0x4b800000, v96
	v_cmp_gt_f32_e32 vcc, s22, v96
	v_pk_mul_f32 v[84:85], v[84:85], v[84:85]
	v_pk_mul_f32 v[88:89], v[80:81], v[80:81]
	v_max_f32_e32 v80, 0, v86
	v_max_f32_e32 v81, 0, v87
	v_cndmask_b32_e32 v82, v96, v82, vcc
	v_pk_mul_f32 v[86:87], v[80:81], v[80:81]
	v_cvt_pk_bf16_f32 v80, v84, v85
	v_rsq_f32_e32 v84, v82
	v_cvt_pk_bf16_f32 v81, v86, v87
	v_cvt_pk_bf16_f32 v82, v88, v89
	v_cvt_pk_bf16_f32 v83, v90, v91
	global_store_dwordx4 v[98:99], v[80:83], off offset:256
	s_nop 1
	v_mul_f32_e32 v80, 0x45800000, v84
	v_cndmask_b32_e32 v80, v84, v80, vcc
	v_pk_mul_f32 v[72:73], v[72:73], v[80:81] op_sel_hi:[1,0]
	v_pk_mul_f32 v[78:79], v[78:79], v[80:81] op_sel_hi:[1,0]
	v_pk_mul_f32 v[76:77], v[76:77], v[80:81] op_sel_hi:[1,0]
	v_pk_mul_f32 v[74:75], v[74:75], v[80:81] op_sel_hi:[1,0]
	v_max_f32_e32 v72, 0, v72
	v_max_f32_e32 v73, 0, v73
	v_lshlrev_b64 v[82:83], 13, v[162:163]
	v_max_f32_e32 v76, 0, v76
	v_max_f32_e32 v77, 0, v77
	v_pk_mul_f32 v[84:85], v[72:73], v[72:73]
	v_max_f32_e32 v72, 0, v78
	v_max_f32_e32 v74, 0, v74
	v_max_f32_e32 v73, 0, v79
	v_max_f32_e32 v75, 0, v75
	v_lshl_add_u64 v[82:83], s[36:37], 0, v[82:83]
	v_pk_mul_f32 v[76:77], v[76:77], v[76:77]
	v_pk_mul_f32 v[78:79], v[72:73], v[72:73]
	v_pk_mul_f32 v[86:87], v[74:75], v[74:75]
	v_pk_mul_f32 v[64:65], v[64:65], v[80:81] op_sel_hi:[1,0]
	v_lshl_add_u64 v[82:83], v[82:83], 0, v[152:153]
	v_cvt_pk_bf16_f32 v72, v76, v77
	v_cvt_pk_bf16_f32 v73, v78, v79
	v_cvt_pk_bf16_f32 v74, v84, v85
	v_cvt_pk_bf16_f32 v75, v86, v87
	v_pk_mul_f32 v[70:71], v[70:71], v[80:81] op_sel_hi:[1,0]
	v_max_f32_e32 v64, 0, v64
	v_max_f32_e32 v65, 0, v65
	global_store_dwordx4 v[82:83], v[72:75], off
	v_pk_mul_f32 v[68:69], v[68:69], v[80:81] op_sel_hi:[1,0]
	v_pk_mul_f32 v[66:67], v[66:67], v[80:81] op_sel_hi:[1,0]
	v_pk_mul_f32 v[72:73], v[64:65], v[64:65]
	v_max_f32_e32 v64, 0, v70
	v_max_f32_e32 v65, 0, v71
	s_waitcnt vmcnt(10)
	v_mov_b32_e32 v70, v141
	v_mov_b32_e32 v71, v142
	v_mov_b32_e32 v141, v143
	s_waitcnt vmcnt(9)
	v_mov_b32_e32 v74, v137
	v_mov_b32_e32 v75, v138
	v_mov_b32_e32 v137, v139
	v_pk_add_f32 v[70:71], v[70:71], v[140:141]
	v_pk_add_f32 v[74:75], v[74:75], v[136:137]
	v_mov_b32_e32 v77, v70
	v_mov_b32_e32 v76, v74
	v_mov_b32_e32 v70, v75
	v_pk_add_f32 v[70:71], v[76:77], v[70:71]
	ds_bpermute_b32 v75, v181, v71
	ds_bpermute_b32 v74, v181, v70
	v_max_f32_e32 v68, 0, v68
	v_max_f32_e32 v69, 0, v69
	v_pk_mul_f32 v[68:69], v[68:69], v[68:69]
	v_pk_mul_f32 v[76:77], v[64:65], v[64:65]
	v_cvt_pk_bf16_f32 v64, v68, v69
	s_waitcnt lgkmcnt(0)
	v_pk_add_f32 v[68:69], v[70:71], v[74:75]
	ds_bpermute_b32 v71, v144, v69
	ds_bpermute_b32 v70, v144, v68
	v_max_f32_e32 v66, 0, v66
	v_max_f32_e32 v67, 0, v67
	v_pk_mul_f32 v[78:79], v[66:67], v[66:67]
	v_cvt_pk_bf16_f32 v65, v76, v77
	v_cvt_pk_bf16_f32 v66, v72, v73
	v_cvt_pk_bf16_f32 v67, v78, v79
	global_store_dwordx4 v[82:83], v[64:67], off offset:256
	s_waitcnt lgkmcnt(0)
; __device__ __forceinline__ unsigned pk2(float lo, float hi) { f32x2_t v = {lo, hi}; bf16x2_t b = __builtin_convertvector(v, bf16x2_t); return __builtin_bit_cast(unsigned, b); }
;     __device__ __forceinline__ void operator()(const f32x4 (&acc)[2][2][4][2], const Unit& u, int wr, int wc, int fr, int fq) const {
;     ...
;             for (int m = 0; m < 4; ++m) { const int row = row0 + ai * HALF + m * 16;
;                 float t = (sp[ai][m][0] + sp[ai][m][1]) + (sp[ai][m][2] + sp[ai][m][3]); t += __shfl_xor(t, 16); t += __shfl_xor(t, 32);
;                 const float rs = rsqrtf(t * (1.0f / DM) + EPS);
;                 bf16_t* rowp = O + (size_t)row * DFF + col0;
; #pragma unroll
;                 for (int bj = 0; bj < 2; ++bj) { f32x4 v0 = acc[ai][bj][m][0] * rs, v1 = acc[ai][bj][m][1] * rs;
; #pragma unroll
;                     for (int e = 0; e < 4; ++e) { v0[e] = fmaxf(v0[e], 0.f); v0[e] *= v0[e]; v1[e] = fmaxf(v1[e], 0.f); v1[e] *= v1[e]; }
;                     u32x4 w; w.x = pk2(v0[0], v0[1]); w.y = pk2(v0[2], v0[3]); w.z = pk2(v1[0], v1[1]); w.w = pk2(v1[2], v1[3]);
;                     *(u32x4*)(rowp + bj * HALF) = w; } }
	s_nop 0
	v_pk_add_f32 v[64:65], v[68:69], v[70:71]
	s_nop 0
	v_pk_fma_f32 v[64:65], v[64:65], s[8:9], v[154:155] op_sel_hi:[1,0,0]
	s_nop 0
	v_mul_f32_e32 v66, 0x4b800000, v65
	v_cmp_gt_f32_e32 vcc, s22, v65
	s_nop 1
	v_cndmask_b32_e32 v65, v65, v66, vcc
	v_rsq_f32_e32 v65, v65
	v_lshlrev_b64 v[66:67], 13, v[160:161]
	v_lshl_add_u64 v[66:67], s[36:37], 0, v[66:67]
	v_lshl_add_u64 v[66:67], v[66:67], 0, v[152:153]
	v_mul_f32_e32 v68, 0x45800000, v65
	v_cndmask_b32_e32 v68, v65, v68, vcc
	v_pk_mul_f32 v[56:57], v[56:57], v[68:69] op_sel_hi:[1,0]
	v_pk_mul_f32 v[62:63], v[62:63], v[68:69] op_sel_hi:[1,0]
	v_pk_mul_f32 v[60:61], v[60:61], v[68:69] op_sel_hi:[1,0]
	v_pk_mul_f32 v[58:59], v[58:59], v[68:69] op_sel_hi:[1,0]
	v_max_f32_e32 v56, 0, v56
	v_max_f32_e32 v57, 0, v57
	v_max_f32_e32 v60, 0, v60
	v_max_f32_e32 v61, 0, v61
	v_pk_mul_f32 v[70:71], v[56:57], v[56:57]
	v_max_f32_e32 v56, 0, v62
	v_max_f32_e32 v58, 0, v58
	v_max_f32_e32 v57, 0, v63
	v_max_f32_e32 v59, 0, v59
	v_pk_mul_f32 v[60:61], v[60:61], v[60:61]
	v_pk_mul_f32 v[62:63], v[56:57], v[56:57]
	v_pk_mul_f32 v[72:73], v[58:59], v[58:59]
	v_pk_mul_f32 v[50:51], v[50:51], v[68:69] op_sel_hi:[1,0]
	v_cvt_pk_bf16_f32 v56, v60, v61
	v_cvt_pk_bf16_f32 v57, v62, v63
	v_cvt_pk_bf16_f32 v58, v70, v71
	v_cvt_pk_bf16_f32 v59, v72, v73
	v_pk_mul_f32 v[52:53], v[52:53], v[68:69] op_sel_hi:[1,0]
	v_pk_mul_f32 v[48:49], v[48:49], v[68:69] op_sel_hi:[1,0]
	v_max_f32_e32 v50, 0, v50
	v_max_f32_e32 v51, 0, v51
	global_store_dwordx4 v[66:67], v[56:59], off
	v_pk_mul_f32 v[54:55], v[54:55], v[68:69] op_sel_hi:[1,0]
	v_max_f32_e32 v52, 0, v52
	v_max_f32_e32 v48, 0, v48
	v_max_f32_e32 v53, 0, v53
	v_max_f32_e32 v49, 0, v49
	v_pk_mul_f32 v[58:59], v[50:51], v[50:51]
	v_mul_f32_e32 v50, 0x4b800000, v64
	v_cmp_gt_f32_e32 vcc, s22, v64
	v_pk_mul_f32 v[52:53], v[52:53], v[52:53]
	v_pk_mul_f32 v[56:57], v[48:49], v[48:49]
	v_max_f32_e32 v48, 0, v54
	v_max_f32_e32 v49, 0, v55
	v_cndmask_b32_e32 v50, v64, v50, vcc
	v_pk_mul_f32 v[54:55], v[48:49], v[48:49]
	v_cvt_pk_bf16_f32 v48, v52, v53
	v_rsq_f32_e32 v52, v50
	v_cvt_pk_bf16_f32 v49, v54, v55
	v_cvt_pk_bf16_f32 v50, v56, v57
	v_cvt_pk_bf16_f32 v51, v58, v59
	global_store_dwordx4 v[66:67], v[48:51], off offset:256
	s_nop 1
	v_mul_f32_e32 v48, 0x45800000, v52
	v_cndmask_b32_e32 v48, v52, v48, vcc
	v_pk_mul_f32 v[40:41], v[40:41], v[48:49] op_sel_hi:[1,0]
	v_pk_mul_f32 v[46:47], v[46:47], v[48:49] op_sel_hi:[1,0]
	v_pk_mul_f32 v[44:45], v[44:45], v[48:49] op_sel_hi:[1,0]
	v_pk_mul_f32 v[42:43], v[42:43], v[48:49] op_sel_hi:[1,0]
	v_max_f32_e32 v40, 0, v40
	v_max_f32_e32 v41, 0, v41
	v_lshlrev_b64 v[50:51], 13, v[158:159]
	v_max_f32_e32 v44, 0, v44
	v_max_f32_e32 v45, 0, v45
	v_pk_mul_f32 v[52:53], v[40:41], v[40:41]
	v_max_f32_e32 v40, 0, v46
	v_max_f32_e32 v42, 0, v42
	v_max_f32_e32 v41, 0, v47
	v_max_f32_e32 v43, 0, v43
	v_lshl_add_u64 v[50:51], s[36:37], 0, v[50:51]
	v_pk_mul_f32 v[44:45], v[44:45], v[44:45]
	v_pk_mul_f32 v[46:47], v[40:41], v[40:41]
	v_pk_mul_f32 v[54:55], v[42:43], v[42:43]
	v_pk_mul_f32 v[32:33], v[32:33], v[48:49] op_sel_hi:[1,0]
	v_lshl_add_u64 v[50:51], v[50:51], 0, v[152:153]
	v_cvt_pk_bf16_f32 v40, v44, v45
	v_cvt_pk_bf16_f32 v41, v46, v47
	v_cvt_pk_bf16_f32 v42, v52, v53
	v_cvt_pk_bf16_f32 v43, v54, v55
	v_pk_mul_f32 v[38:39], v[38:39], v[48:49] op_sel_hi:[1,0]
	v_max_f32_e32 v32, 0, v32
	v_max_f32_e32 v33, 0, v33
	global_store_dwordx4 v[50:51], v[40:43], off
	v_pk_mul_f32 v[36:37], v[36:37], v[48:49] op_sel_hi:[1,0]
	v_pk_mul_f32 v[34:35], v[34:35], v[48:49] op_sel_hi:[1,0]
	v_pk_mul_f32 v[40:41], v[32:33], v[32:33]
	v_max_f32_e32 v32, 0, v38
	v_max_f32_e32 v33, 0, v39
	s_waitcnt vmcnt(12)
	v_mov_b32_e32 v38, v133
	v_mov_b32_e32 v39, v134
	v_mov_b32_e32 v133, v135
	s_waitcnt vmcnt(11)
	v_mov_b32_e32 v42, v129
	v_mov_b32_e32 v43, v130
	v_mov_b32_e32 v129, v131
	v_pk_add_f32 v[38:39], v[38:39], v[132:133]
	v_pk_add_f32 v[42:43], v[42:43], v[128:129]
	v_mov_b32_e32 v45, v38
	v_mov_b32_e32 v44, v42
	v_mov_b32_e32 v38, v43
	v_pk_add_f32 v[38:39], v[44:45], v[38:39]
	ds_bpermute_b32 v43, v181, v39
	ds_bpermute_b32 v42, v181, v38
	v_max_f32_e32 v36, 0, v36
	v_max_f32_e32 v37, 0, v37
	v_pk_mul_f32 v[36:37], v[36:37], v[36:37]
	v_pk_mul_f32 v[44:45], v[32:33], v[32:33]
	v_cvt_pk_bf16_f32 v32, v36, v37
	s_waitcnt lgkmcnt(0)
	v_pk_add_f32 v[36:37], v[38:39], v[42:43]
	ds_bpermute_b32 v39, v144, v37
	ds_bpermute_b32 v38, v144, v36
	v_max_f32_e32 v34, 0, v34
	v_max_f32_e32 v35, 0, v35
	v_pk_mul_f32 v[46:47], v[34:35], v[34:35]
	v_cvt_pk_bf16_f32 v33, v44, v45
	v_cvt_pk_bf16_f32 v34, v40, v41
	v_cvt_pk_bf16_f32 v35, v46, v47
	global_store_dwordx4 v[50:51], v[32:35], off offset:256
	s_waitcnt lgkmcnt(0)
; __device__ __forceinline__ unsigned pk2(float lo, float hi) { f32x2_t v = {lo, hi}; bf16x2_t b = __builtin_convertvector(v, bf16x2_t); return __builtin_bit_cast(unsigned, b); }
;     __device__ __forceinline__ bool next(int i, Unit& u) const {
;         const int ti = (NSUB == 1) ? i : i / NSUB, sub = (NSUB == 1) ? 0 : i - ti * NSUB;
;         const long L = (long)ti * G + c; if (L >= (long)nM * nN) return false;
;         tile_of((int)L, nM, nN, u.pm, u.pn);
;     __device__ __forceinline__ void operator()(const f32x4 (&acc)[2][2][4][2], const Unit& u, int wr, int wc, int fr, int fq) const {
;     ...
;             for (int m = 0; m < 4; ++m) { const int row = row0 + ai * HALF + m * 16;
;                 float t = (sp[ai][m][0] + sp[ai][m][1]) + (sp[ai][m][2] + sp[ai][m][3]); t += __shfl_xor(t, 16); t += __shfl_xor(t, 32);
;                 const float rs = rsqrtf(t * (1.0f / DM) + EPS);
;                 bf16_t* rowp = O + (size_t)row * DFF + col0;
; #pragma unroll
;                 for (int bj = 0; bj < 2; ++bj) { f32x4 v0 = acc[ai][bj][m][0] * rs, v1 = acc[ai][bj][m][1] * rs;
; #pragma unroll
;                     for (int e = 0; e < 4; ++e) { v0[e] = fmaxf(v0[e], 0.f); v0[e] *= v0[e]; v1[e] = fmaxf(v1[e], 0.f); v1[e] *= v1[e]; }
;                     u32x4 w; w.x = pk2(v0[0], v0[1]); w.y = pk2(v0[2], v0[3]); w.z = pk2(v1[0], v1[1]); w.w = pk2(v1[2], v1[3]);
;                     *(u32x4*)(rowp + bj * HALF) = w; } }
	s_nop 0
	v_pk_add_f32 v[32:33], v[36:37], v[38:39]
	s_nop 0
	v_pk_fma_f32 v[32:33], v[32:33], s[8:9], v[154:155] op_sel_hi:[1,0,0]
	s_nop 0
	v_mul_f32_e32 v34, 0x4b800000, v33
	v_cmp_gt_f32_e32 vcc, s22, v33
	s_nop 1
	v_cndmask_b32_e32 v33, v33, v34, vcc
	v_rsq_f32_e32 v33, v33
	v_lshlrev_b64 v[34:35], 13, v[156:157]
	v_lshl_add_u64 v[34:35], s[36:37], 0, v[34:35]
	v_lshl_add_u64 v[34:35], v[34:35], 0, v[152:153]
	v_mul_f32_e32 v36, 0x45800000, v33
	v_cndmask_b32_e32 v36, v33, v36, vcc
	v_pk_mul_f32 v[24:25], v[24:25], v[36:37] op_sel_hi:[1,0]
	v_pk_mul_f32 v[30:31], v[30:31], v[36:37] op_sel_hi:[1,0]
	v_pk_mul_f32 v[28:29], v[28:29], v[36:37] op_sel_hi:[1,0]
	v_pk_mul_f32 v[26:27], v[26:27], v[36:37] op_sel_hi:[1,0]
	v_max_f32_e32 v24, 0, v24
	v_max_f32_e32 v25, 0, v25
	v_max_f32_e32 v28, 0, v28
	v_max_f32_e32 v29, 0, v29
	v_pk_mul_f32 v[38:39], v[24:25], v[24:25]
	v_max_f32_e32 v24, 0, v30
	v_max_f32_e32 v26, 0, v26
	v_max_f32_e32 v25, 0, v31
	v_max_f32_e32 v27, 0, v27
	v_pk_mul_f32 v[28:29], v[28:29], v[28:29]
	v_pk_mul_f32 v[30:31], v[24:25], v[24:25]
	v_pk_mul_f32 v[40:41], v[26:27], v[26:27]
	v_pk_mul_f32 v[18:19], v[18:19], v[36:37] op_sel_hi:[1,0]
	v_cvt_pk_bf16_f32 v24, v28, v29
	v_cvt_pk_bf16_f32 v25, v30, v31
	v_cvt_pk_bf16_f32 v26, v38, v39
	v_cvt_pk_bf16_f32 v27, v40, v41
	v_pk_mul_f32 v[20:21], v[20:21], v[36:37] op_sel_hi:[1,0]
	v_pk_mul_f32 v[16:17], v[16:17], v[36:37] op_sel_hi:[1,0]
	v_max_f32_e32 v18, 0, v18
	v_max_f32_e32 v19, 0, v19
	global_store_dwordx4 v[34:35], v[24:27], off
	v_pk_mul_f32 v[22:23], v[22:23], v[36:37] op_sel_hi:[1,0]
	v_max_f32_e32 v20, 0, v20
	v_max_f32_e32 v16, 0, v16
	v_max_f32_e32 v21, 0, v21
	v_max_f32_e32 v17, 0, v17
	v_pk_mul_f32 v[26:27], v[18:19], v[18:19]
	v_mul_f32_e32 v18, 0x4b800000, v32
	v_cmp_gt_f32_e32 vcc, s22, v32
	v_pk_mul_f32 v[20:21], v[20:21], v[20:21]
	v_pk_mul_f32 v[24:25], v[16:17], v[16:17]
	v_max_f32_e32 v16, 0, v22
	v_max_f32_e32 v17, 0, v23
	v_cndmask_b32_e32 v18, v32, v18, vcc
	v_pk_mul_f32 v[22:23], v[16:17], v[16:17]
	v_cvt_pk_bf16_f32 v16, v20, v21
	v_rsq_f32_e32 v20, v18
	v_cvt_pk_bf16_f32 v17, v22, v23
	v_cvt_pk_bf16_f32 v18, v24, v25
	v_cvt_pk_bf16_f32 v19, v26, v27
	global_store_dwordx4 v[34:35], v[16:19], off offset:256
	s_nop 1
	v_mul_f32_e32 v16, 0x45800000, v20
	v_cndmask_b32_e32 v16, v20, v16, vcc
	v_pk_mul_f32 v[8:9], v[8:9], v[16:17] op_sel_hi:[1,0]
	v_pk_mul_f32 v[14:15], v[14:15], v[16:17] op_sel_hi:[1,0]
	v_pk_mul_f32 v[12:13], v[12:13], v[16:17] op_sel_hi:[1,0]
	v_pk_mul_f32 v[10:11], v[10:11], v[16:17] op_sel_hi:[1,0]
	v_max_f32_e32 v8, 0, v8
	v_max_f32_e32 v9, 0, v9
	v_lshlrev_b64 v[18:19], 13, v[150:151]
	v_max_f32_e32 v12, 0, v12
	v_max_f32_e32 v13, 0, v13
	v_pk_mul_f32 v[20:21], v[8:9], v[8:9]
	v_max_f32_e32 v8, 0, v14
	v_max_f32_e32 v10, 0, v10
	v_max_f32_e32 v9, 0, v15
	v_max_f32_e32 v11, 0, v11
	v_lshl_add_u64 v[18:19], s[36:37], 0, v[18:19]
	v_pk_mul_f32 v[12:13], v[12:13], v[12:13]
	v_pk_mul_f32 v[14:15], v[8:9], v[8:9]
	v_pk_mul_f32 v[22:23], v[10:11], v[10:11]
	v_pk_mul_f32 v[0:1], v[0:1], v[16:17] op_sel_hi:[1,0]
	v_lshl_add_u64 v[18:19], v[18:19], 0, v[152:153]
	v_cvt_pk_bf16_f32 v8, v12, v13
	v_cvt_pk_bf16_f32 v9, v14, v15
	v_cvt_pk_bf16_f32 v10, v20, v21
	v_cvt_pk_bf16_f32 v11, v22, v23
	v_pk_mul_f32 v[6:7], v[6:7], v[16:17] op_sel_hi:[1,0]
	v_pk_mul_f32 v[4:5], v[4:5], v[16:17] op_sel_hi:[1,0]
	v_pk_mul_f32 v[2:3], v[2:3], v[16:17] op_sel_hi:[1,0]
	v_max_f32_e32 v0, 0, v0
	v_max_f32_e32 v1, 0, v1
	global_store_dwordx4 v[18:19], v[8:11], off
	v_max_f32_e32 v4, 0, v4
	v_max_f32_e32 v5, 0, v5
	v_pk_mul_f32 v[8:9], v[0:1], v[0:1]
	v_max_f32_e32 v0, 0, v6
	v_max_f32_e32 v2, 0, v2
	v_max_f32_e32 v1, 0, v7
	v_max_f32_e32 v3, 0, v3
	v_pk_mul_f32 v[4:5], v[4:5], v[4:5]
	v_pk_mul_f32 v[6:7], v[0:1], v[0:1]
	v_pk_mul_f32 v[10:11], v[2:3], v[2:3]
	v_cvt_pk_bf16_f32 v0, v4, v5
	v_cvt_pk_bf16_f32 v1, v6, v7
	v_cvt_pk_bf16_f32 v2, v8, v9
	v_cvt_pk_bf16_f32 v3, v10, v11
	s_and_b64 vcc, exec, s[4:5]
	global_store_dwordx4 v[18:19], v[0:3], off offset:256
	s_cbranch_vccnz .LBB0_900
	s_andn2_b64 vcc, exec, s[96:97]
	s_cbranch_vccz .Lp5_al_post
	s_barrier
.Lp5_al_post:
.LBB0_895:
	s_add_i32 s13, s13, 1
	s_mul_i32 s4, s13, s29
	s_mul_hi_u32 s5, s13, s28
	s_add_i32 s5, s5, s4
	s_mul_i32 s4, s13, s28
	s_add_u32 s52, s4, s84
	s_addc_u32 s53, s5, s85
	v_cmp_gt_i64_e64 s[4:5], s[52:53], v[148:149]
	s_and_b64 vcc, exec, s[4:5]
	s_cbranch_vccnz .LBB0_897
	s_ashr_i32 s14, s52, 31
	s_lshr_b32 s14, s14, 29
	s_add_i32 s14, s52, s14
	s_ashr_i32 s15, s14, 3
	s_and_b32 s14, s14, -8
	s_sub_i32 s14, s52, s14
	s_cmp_lt_i32 s14, 0
	s_cselect_b32 s16, s9, 0x280
	s_mul_i32 s14, s14, s16
	s_add_i32 s14, s14, s15
	s_ashr_i32 s15, s14, 31
	s_lshr_b32 s15, s15, 25
	s_add_i32 s15, s14, s15
	s_ashr_i32 s16, s15, 7
	s_lshl_b32 s16, s16, 3
	s_sub_i32 s17, 0x140, s16
	s_min_i32 s17, s17, 8
	s_abs_i32 s21, s17
	v_cvt_f32_u32_e32 v0, s21
	s_sub_i32 s24, 0, s21
	s_and_b32 s15, s15, 0xffffff80
	s_sub_i32 s15, s14, s15
	v_rcp_iflag_f32_e32 v0, v0
	s_abs_i32 s14, s15
	s_xor_b32 s23, s15, s17
	s_ashr_i32 s23, s23, 31
	v_mul_f32_e32 v0, 0x4f7ffffe, v0
	v_cvt_u32_f32_e32 v0, v0
	s_nop 0
	v_readfirstlane_b32 s25, v0
	s_mul_i32 s24, s24, s25
	s_mul_hi_u32 s24, s25, s24
	s_add_i32 s25, s25, s24
	s_mul_hi_u32 s24, s14, s25
	s_mul_i32 s25, s24, s21
	s_sub_i32 s14, s14, s25
	s_add_i32 s26, s24, 1
	s_sub_i32 s25, s14, s21
	s_cmp_ge_u32 s14, s21
	s_cselect_b32 s24, s26, s24
	s_cselect_b32 s14, s25, s14
	s_add_i32 s25, s24, 1
	s_cmp_ge_u32 s14, s21
	s_cselect_b32 s14, s25, s24
	s_xor_b32 s14, s14, s23
	s_sub_i32 s14, s14, s23
	s_mul_i32 s17, s14, s17
	s_sub_i32 s15, s15, s17
	s_add_i32 s26, s16, s15
	s_mov_b32 s23, 16

; #define PG8_WAIT_V(n) asm volatile("s_waitcnt vmcnt(" #n ")" ::: "memory")
; #define PG8_BAR __builtin_amdgcn_s_barrier()
; template <class Epi, class SchedT, bool ALIGN_EPI, bool SP2, bool FP8 = false>
; __device__ __forceinline__ void gemm_phase(LAS unsigned char* lds, const Gemm g, const SchedT& S, const Epi& E, const int wid) {
;     ...
;     PG8_WAIT_V(0);
;     if constexpr (!ALIGN_EPI) { if (wr == 0) PG8_BAR; }
;     PG8_BAR;
.LBB0_900:
	s_waitcnt vmcnt(0)
	s_andn2_b64 vcc, exec, s[96:97]
	s_cbranch_vccnz .LBB0_902
.LBB0_902:
	s_barrier
